# MLA attention: tile pairs wholly below the diagonal run in a peeled fast loop (no activity logic, MFMA segment opens with its first MFMA, stores/reads/scalar work/next loads in MFMA issue shadows)
# speedup vs baseline: 1.0105x; 1.0069x over previous
; #define ATT_BAR() do { asm volatile("s_waitcnt lgkmcnt(0)" ::: "memory"); __builtin_amdgcn_s_barrier(); asm volatile("" ::: "memory"); } while (0)
; template <int DK, int DV>
; __device__ __forceinline__ void attn_unit(LAS unsigned char* lds, const bf16* Qp, int ldq, const bf16* Kp, int ldk, const bf16* VTp, bf16* Op, int ldo, int qb) {
;     ...
;     ATT_LOAD(0, kra, vra); ATT_LOAD(1, krb, vrb);
;     ATT_STORE(0, kra, vra); ATT_STORE(BUF, krb, vrb);
;     ATT_LOAD(2, krb, vrb);
;     __syncthreads();
;     float mrun = 0.f, lrun = 0.f;
;     f32x16 o[NDB];
; #pragma unroll
;     for (int db = 0; db < NDB; ++db)
; #pragma unroll
;         for (int r = 0; r < 16; ++r) o[db][r] = 0.f;
;     f32x16 s0, s1;
;     const f32x16 zacc = {0.f, 0.f, 0.f, 0.f, 0.f, 0.f, 0.f, 0.f, 0.f, 0.f, 0.f, 0.f, 0.f, 0.f, 0.f, 0.f};
;     f32x16 negm = zacc;
;     constexpr float ATT_THR = 8.f;
;     ATT_QK(0, zacc);
;     if (grpB) ATT_BAR();
;     int bcur = 0, bnext = BUF, bfree = 2 * BUF;
; #pragma unroll 1
;     for (int t = 0; t < NT; t += 2) {
.LBB0_1036:
	ds_read_b128 v[196:199], v141
	ds_read_b128 v[200:203], v141 offset:1024
	ds_read_b128 v[204:207], v141 offset:2048
	ds_read_b128 v[208:211], v141 offset:3072
	ds_read_b128 v[212:215], v141 offset:4096
	ds_read_b128 v[216:219], v141 offset:5120
	v_or_b32_e32 v159, s46, v6
	v_mul_u32_u24_e32 v6, 0x90, v6
	v_lshlrev_b32_e32 v158, 2, v7
	v_lshl_add_u64 v[144:145], v[2:3], 1, s[4:5]
	v_lshl_add_u64 v[146:147], v[4:5], 1, s[4:5]
	v_mad_i64_i32 v[186:187], vcc, v150, s3, v[144:145]
	v_mad_i64_i32 v[188:189], vcc, v151, s3, v[146:147]
	v_add3_u32 v160, 0, v6, v0
	v_mov_b32_e32 v2, v1
	v_mov_b32_e32 v3, v1
	v_mov_b32_e32 v4, v1
	v_mov_b32_e32 v5, v1
	v_mov_b32_e32 v6, v1
	v_mov_b32_e32 v7, v1
	v_mov_b32_e32 v8, v1
	v_mov_b32_e32 v9, v1
	v_mov_b32_e32 v10, v1
	v_mov_b32_e32 v11, v1
	v_mov_b32_e32 v12, v1
	v_mov_b32_e32 v13, v1
	v_mov_b32_e32 v14, v1
	v_mov_b32_e32 v15, v1
	v_mov_b32_e32 v16, v1
	v_mov_b32_e32 v17, v1
	v_mov_b32_e32 v18, v1
	v_mov_b32_e32 v19, v1
	v_mov_b32_e32 v20, v1
	v_mov_b32_e32 v21, v1
	v_mov_b32_e32 v22, v1
	v_mov_b32_e32 v23, v1
	v_mov_b32_e32 v24, v1
	v_mov_b32_e32 v25, v1
	v_mov_b32_e32 v26, v1
	v_mov_b32_e32 v27, v1
	v_mov_b32_e32 v28, v1
	v_mov_b32_e32 v29, v1
	v_mov_b32_e32 v30, v1
	v_mov_b32_e32 v31, v1
	s_lshl_b32 s48, s0, 2
	v_mov_b32_e32 v0, v1
	v_mov_b64_e32 v[32:33], v[30:31]
	s_lshl_b32 s47, s1, 13
	v_ashrrev_i32_e32 v139, 31, v138
	s_add_i32 s49, s48, 4
	s_or_b32 s50, s48, 3
	s_or_b32 s51, s46, 31
	s_mov_b32 s54, 0
	s_sub_i32 s55, 0, s48
	s_sub_i32 s56, 0, s8
	v_subrev_u32_e32 v161, s8, v158
	v_mov_b32_e32 v66, v1
	v_mov_b32_e32 v67, v1
	v_mov_b32_e32 v68, v1
	v_mov_b32_e32 v69, v1
	v_mov_b32_e32 v70, v1
	v_mov_b32_e32 v71, v1
	v_mov_b32_e32 v72, v1
	v_mov_b32_e32 v73, v1
	v_mov_b32_e32 v74, v1
	v_mov_b32_e32 v75, v1
	v_mov_b32_e32 v76, v1
	v_mov_b32_e32 v77, v1
	v_mov_b32_e32 v78, v1
	v_mov_b32_e32 v79, v1
	v_mov_b32_e32 v80, v1
	v_mov_b32_e32 v81, v1
	s_mov_b32 s57, 0xb000
	s_movk_i32 s58, 0x5800
	v_mov_b32_e32 v162, 0
	v_mov_b32_e32 v163, 0
	s_mov_b32 s0, 0
	s_mov_b32 s59, 0
	v_mov_b64_e32 v[30:31], v[28:29]
	v_mov_b64_e32 v[28:29], v[26:27]
	v_mov_b64_e32 v[26:27], v[24:25]
	v_mov_b64_e32 v[24:25], v[22:23]
	v_mov_b64_e32 v[22:23], v[20:21]
	v_mov_b64_e32 v[20:21], v[18:19]
	v_mov_b64_e32 v[18:19], v[16:17]
	v_mov_b64_e32 v[16:17], v[14:15]
	v_mov_b64_e32 v[14:15], v[12:13]
	v_mov_b64_e32 v[12:13], v[10:11]
	v_mov_b64_e32 v[10:11], v[8:9]
	v_mov_b64_e32 v[8:9], v[6:7]
	v_mov_b64_e32 v[6:7], v[4:5]
	v_mov_b64_e32 v[4:5], v[2:3]
	v_mov_b64_e32 v[2:3], v[0:1]
	s_add_i32 s1, s59, 3
	s_cmp_lt_u32 s1, s49
	s_cselect_b32 s1, s1, s50
	s_lshl_b32 s8, s1, 6
	s_mul_i32 s4, s8, 0x600
	s_mov_b32 s5, 0
	v_lshl_add_u64 v[94:95], s[4:5], 0, v[186:187]
	v_lshl_add_u64 v[96:97], s[4:5], 0, v[188:189]
	v_lshl_add_u64 v[102:103], s[8:9], 1, v[142:143]
	global_load_dwordx4 v[98:101], v[94:95], off
	s_nop 0
	global_load_dwordx4 v[94:97], v[96:97], off
	global_load_dwordx4 v[102:105], v[102:103], off
	s_add_i32 s4, s55, s59
	s_cmp_lt_i32 s4, -2
	s_cbranch_scc1 .Lfm_entry

.Lfm_entry:
	s_mov_b32 s60, s58
	s_mov_b32 s58, s0
.Lfm_head:
	v_add_u32_e32 v248, s58, v160
	ds_read_b128 v[164:167], v248 offset:13312
	ds_read_b128 v[168:171], v248 offset:17920
	ds_read_b128 v[172:175], v248 offset:13344
	ds_read_b128 v[176:179], v248 offset:17952
	ds_read_b128 v[180:183], v248 offset:13376
	ds_read_b128 v[220:223], v248 offset:17984
	ds_read_b128 v[224:227], v248 offset:13408
	ds_read_b128 v[232:235], v248 offset:18016
	v_max3_f32 v0, v34, v35, v36
	v_max3_f32 v122, v50, v51, v52
	v_max3_f32 v0, v0, v37, v38
	v_max3_f32 v122, v122, v53, v54
	v_max3_f32 v0, v0, v39, v40
	v_max3_f32 v122, v122, v55, v56
	v_max3_f32 v0, v0, v41, v42
	v_max3_f32 v122, v122, v57, v58
	v_max3_f32 v0, v0, v43, v44
	v_max3_f32 v122, v122, v59, v60
	v_max3_f32 v0, v0, v45, v46
	v_max3_f32 v122, v122, v61, v62
	v_max_f32_e32 v123, v65, v65
	v_max_f32_e32 v124, v49, v49
	v_max3_f32 v0, v0, v47, v48
	v_max3_f32 v122, v122, v63, v64
	v_max_f32_e32 v123, v124, v123
	v_max3_f32 v0, v0, v122, v123
	s_cmp_lg_u32 s54, 0
	s_cselect_b64 s[20:21], -1, 0
	s_cmp_eq_u32 s54, 0
	s_cbranch_scc1 .Lfm_a_xchg
	v_cmp_lt_f32_e32 vcc, s35, v0
	s_cbranch_vccnz .Lfm_a_xchg
.Lfm_a_exp:
	v_exp_f32_e32 v34, v34
	v_exp_f32_e32 v50, v50
	v_exp_f32_e32 v35, v35
	v_exp_f32_e32 v51, v51
	v_exp_f32_e32 v42, v42
	v_exp_f32_e32 v58, v58
	v_exp_f32_e32 v43, v43
	v_exp_f32_e32 v59, v59
	v_exp_f32_e32 v36, v36
	v_exp_f32_e32 v52, v52
	v_exp_f32_e32 v37, v37
	v_exp_f32_e32 v53, v53
	v_exp_f32_e32 v44, v44
	v_exp_f32_e32 v60, v60
	v_exp_f32_e32 v45, v45
	v_exp_f32_e32 v61, v61
	v_exp_f32_e32 v38, v38
	v_exp_f32_e32 v54, v54
	v_exp_f32_e32 v39, v39
	v_exp_f32_e32 v55, v55
	v_exp_f32_e32 v46, v46
	v_exp_f32_e32 v62, v62
	v_exp_f32_e32 v47, v47
	v_exp_f32_e32 v63, v63
	v_exp_f32_e32 v40, v40
	v_exp_f32_e32 v56, v56
	v_exp_f32_e32 v41, v41
	v_exp_f32_e32 v57, v57
	v_exp_f32_e32 v48, v48
	v_exp_f32_e32 v64, v64
	v_exp_f32_e32 v49, v49
	v_exp_f32_e32 v65, v65
	v_pk_add_f32 v[122:123], v[34:35], v[50:51]
	v_pk_add_f32 v[124:125], v[36:37], v[52:53]
	v_pk_add_f32 v[126:127], v[38:39], v[54:55]
	v_pk_add_f32 v[128:129], v[40:41], v[56:57]
	v_pk_add_f32 v[130:131], v[42:43], v[58:59]
	v_pk_add_f32 v[132:133], v[44:45], v[60:61]
	v_pk_add_f32 v[134:135], v[46:47], v[62:63]
	v_pk_add_f32 v[136:137], v[48:49], v[64:65]
	v_pk_add_f32 v[122:123], v[122:123], v[124:125]
	v_pk_add_f32 v[126:127], v[126:127], v[128:129]
	v_pk_add_f32 v[130:131], v[130:131], v[132:133]
	v_pk_add_f32 v[134:135], v[134:135], v[136:137]
	v_pk_add_f32 v[122:123], v[122:123], v[126:127]
	v_pk_add_f32 v[130:131], v[130:131], v[134:135]
	v_pk_add_f32 v[122:123], v[122:123], v[130:131]
	v_add_f32_e32 v0, v122, v123
	v_cvt_pk_bf16_f32 v122, v34, v35
	v_cvt_pk_bf16_f32 v123, v36, v37
	v_cvt_pk_bf16_f32 v124, v38, v39
	v_cvt_pk_bf16_f32 v125, v40, v41
	v_cvt_pk_bf16_f32 v126, v42, v43
	v_cvt_pk_bf16_f32 v127, v44, v45
	v_cvt_pk_bf16_f32 v128, v46, v47
	v_cvt_pk_bf16_f32 v129, v48, v49
	v_cvt_pk_bf16_f32 v130, v50, v51
	v_cvt_pk_bf16_f32 v131, v52, v53
	v_cvt_pk_bf16_f32 v132, v54, v55
	v_cvt_pk_bf16_f32 v133, v56, v57
	v_cvt_pk_bf16_f32 v134, v58, v59
	v_cvt_pk_bf16_f32 v135, v60, v61
	v_cvt_pk_bf16_f32 v136, v62, v63
	v_cvt_pk_bf16_f32 v137, v64, v65
	v_add_f32_e32 v162, v162, v0
	s_waitcnt lgkmcnt(0)
	s_barrier
	v_mfma_f32_32x32x16_bf16 v[2:17], v[164:167], v[122:125], v[2:17]
	s_setprio 1
	v_add3_u32 v0, s57, v152, v153
	s_waitcnt vmcnt(4)
	ds_write_b128 v0, v[86:89]
	v_mfma_f32_32x32x16_bf16 v[18:33], v[168:171], v[122:125], v[18:33]
	v_add3_u32 v0, s57, v154, v155
	s_waitcnt vmcnt(3)
	ds_write_b128 v0, v[90:93]
	v_mfma_f32_32x32x16_bf16 v[2:17], v[172:175], v[126:129], v[2:17]
	v_add3_u32 v0, s57, v156, v140
	ds_write_b128 v0, v[82:85] offset:13312
	v_add_u32_e32 v249, s60, v157
	v_mfma_f32_32x32x16_bf16 v[18:33], v[176:179], v[126:129], v[18:33]
	ds_read_b128 v[236:239], v249
	ds_read_b128 v[240:243], v249 offset:6656
	ds_read_b128 v[244:247], v249 offset:32
	v_mfma_f32_32x32x16_bf16 v[2:17], v[180:183], v[130:133], v[2:17]
	ds_read_b128 v[164:167], v249 offset:6688
	ds_read_b128 v[168:171], v249 offset:64
	ds_read_b128 v[172:175], v249 offset:6720
	v_mfma_f32_32x32x16_bf16 v[18:33], v[220:223], v[130:133], v[18:33]
	ds_read_b128 v[176:179], v249 offset:96
	ds_read_b128 v[180:183], v249 offset:6752
	ds_read_b128 v[220:223], v249 offset:128
	v_mfma_f32_32x32x16_bf16 v[2:17], v[224:227], v[134:137], v[2:17]
	ds_read_b128 v[224:227], v249 offset:6784
	v_mfma_f32_32x32x16_bf16 v[18:33], v[232:235], v[134:137], v[18:33]
	ds_read_b128 v[232:235], v249 offset:160
	s_waitcnt lgkmcnt(9)
	v_mfma_f32_32x32x16_bf16 v[34:49], v[236:239], v[196:199], v[66:81]
	ds_read_b128 v[236:239], v249 offset:6816
	s_add_i32 s0, s59, 4
	s_cmp_lt_u32 s59, s48
	v_mfma_f32_32x32x16_bf16 v[50:65], v[240:243], v[196:199], v[66:81]
	s_cselect_b32 s0, s0, s50
	s_lshl_b32 s8, s0, 6
	s_mul_i32 s0, s8, 0x600
	s_waitcnt lgkmcnt(7)
	v_mfma_f32_32x32x16_bf16 v[34:49], v[244:247], v[200:203], v[34:49]
	s_mov_b32 s1, 0
	v_lshl_add_u64 v[82:83], s[0:1], 0, v[186:187]
	v_lshl_add_u64 v[84:85], s[0:1], 0, v[188:189]
	v_mfma_f32_32x32x16_bf16 v[50:65], v[164:167], v[200:203], v[50:65]
	global_load_dwordx4 v[86:89], v[82:83], off
	global_load_dwordx4 v[90:93], v[84:85], off
	v_lshl_add_u64 v[82:83], s[8:9], 1, v[142:143]
	v_mfma_f32_32x32x16_bf16 v[34:49], v[168:171], v[204:207], v[34:49]
	global_load_dwordx4 v[82:85], v[82:83], off
	s_waitcnt lgkmcnt(4)
	v_mfma_f32_32x32x16_bf16 v[50:65], v[172:175], v[204:207], v[50:65]
	v_mfma_f32_32x32x16_bf16 v[34:49], v[176:179], v[208:211], v[34:49]
	v_mfma_f32_32x32x16_bf16 v[50:65], v[180:183], v[208:211], v[50:65]
	s_waitcnt lgkmcnt(1)
	v_mfma_f32_32x32x16_bf16 v[34:49], v[220:223], v[212:215], v[34:49]
	v_mfma_f32_32x32x16_bf16 v[50:65], v[224:227], v[212:215], v[50:65]
	v_mfma_f32_32x32x16_bf16 v[34:49], v[232:235], v[216:219], v[34:49]
	s_waitcnt lgkmcnt(0)
	v_mfma_f32_32x32x16_bf16 v[50:65], v[236:239], v[216:219], v[50:65]
	s_setprio 0
	s_waitcnt lgkmcnt(0)
	s_barrier
	v_add_u32_e32 v248, s60, v160
	ds_read_b128 v[164:167], v248 offset:13312
	ds_read_b128 v[168:171], v248 offset:17920
	ds_read_b128 v[172:175], v248 offset:13344
	ds_read_b128 v[176:179], v248 offset:17952
	ds_read_b128 v[180:183], v248 offset:13376
	ds_read_b128 v[220:223], v248 offset:17984
	ds_read_b128 v[224:227], v248 offset:13408
	ds_read_b128 v[232:235], v248 offset:18016
	v_max3_f32 v0, v34, v35, v36
	v_max3_f32 v106, v50, v51, v52
	v_max3_f32 v0, v0, v37, v38
	v_max3_f32 v106, v106, v53, v54
	v_max3_f32 v0, v0, v39, v40
	v_max3_f32 v106, v106, v55, v56
	v_max3_f32 v0, v0, v41, v42
	v_max3_f32 v106, v106, v57, v58
	v_max3_f32 v0, v0, v43, v44
	v_max3_f32 v106, v106, v59, v60
	v_max3_f32 v0, v0, v45, v46
	v_max3_f32 v106, v106, v61, v62
	v_max_f32_e32 v107, v65, v65
	v_max_f32_e32 v108, v49, v49
	v_max3_f32 v0, v0, v47, v48
	v_max3_f32 v106, v106, v63, v64
	v_max_f32_e32 v107, v108, v107
	v_max3_f32 v0, v0, v106, v107
	v_cmp_lt_f32_e32 vcc, s35, v0
	s_cbranch_vccnz .Lfm_b_resc
; template <int DK, int DV>
; __device__ __forceinline__ void attn_unit(LAS unsigned char* lds, const bf16* Qp, int ldq, const bf16* Kp, int ldk, const bf16* VTp, bf16* Op, int ldo, int qb) {
;     ...
;     for (int t = 0; t < NT; t += 2) {
;         ATT_STEP(t, kra, vra, krb, vrb);
;         ATT_STEP(t + 1, krb, vrb, kra, vra);
;     }
.Lfm_b_exp:
	v_exp_f32_e32 v34, v34
	v_exp_f32_e32 v50, v50
	v_exp_f32_e32 v35, v35
	v_exp_f32_e32 v51, v51
	v_exp_f32_e32 v42, v42
	v_exp_f32_e32 v58, v58
	v_exp_f32_e32 v43, v43
	v_exp_f32_e32 v59, v59
	v_exp_f32_e32 v36, v36
	v_exp_f32_e32 v52, v52
	v_exp_f32_e32 v37, v37
	v_exp_f32_e32 v53, v53
	v_exp_f32_e32 v44, v44
	v_exp_f32_e32 v60, v60
	v_exp_f32_e32 v45, v45
	v_exp_f32_e32 v61, v61
	v_exp_f32_e32 v38, v38
	v_exp_f32_e32 v54, v54
	v_exp_f32_e32 v39, v39
	v_exp_f32_e32 v55, v55
	v_exp_f32_e32 v46, v46
	v_exp_f32_e32 v62, v62
	v_exp_f32_e32 v47, v47
	v_exp_f32_e32 v63, v63
	v_exp_f32_e32 v40, v40
	v_exp_f32_e32 v56, v56
	v_exp_f32_e32 v41, v41
	v_exp_f32_e32 v57, v57
	v_exp_f32_e32 v48, v48
	v_exp_f32_e32 v64, v64
	v_exp_f32_e32 v49, v49
	v_exp_f32_e32 v65, v65
	v_pk_add_f32 v[106:107], v[34:35], v[50:51]
	v_pk_add_f32 v[108:109], v[36:37], v[52:53]
	v_pk_add_f32 v[110:111], v[38:39], v[54:55]
	v_pk_add_f32 v[112:113], v[40:41], v[56:57]
	v_pk_add_f32 v[114:115], v[42:43], v[58:59]
	v_pk_add_f32 v[116:117], v[44:45], v[60:61]
	v_pk_add_f32 v[118:119], v[46:47], v[62:63]
	v_pk_add_f32 v[120:121], v[48:49], v[64:65]
	v_pk_add_f32 v[106:107], v[106:107], v[108:109]
	v_pk_add_f32 v[110:111], v[110:111], v[112:113]
	v_pk_add_f32 v[114:115], v[114:115], v[116:117]
	v_pk_add_f32 v[118:119], v[118:119], v[120:121]
	v_pk_add_f32 v[106:107], v[106:107], v[110:111]
	v_pk_add_f32 v[114:115], v[114:115], v[118:119]
	v_pk_add_f32 v[106:107], v[106:107], v[114:115]
	v_add_f32_e32 v0, v106, v107
	v_cvt_pk_bf16_f32 v106, v34, v35
	v_cvt_pk_bf16_f32 v107, v36, v37
	v_cvt_pk_bf16_f32 v108, v38, v39
	v_cvt_pk_bf16_f32 v109, v40, v41
	v_cvt_pk_bf16_f32 v110, v42, v43
	v_cvt_pk_bf16_f32 v111, v44, v45
	v_cvt_pk_bf16_f32 v112, v46, v47
	v_cvt_pk_bf16_f32 v113, v48, v49
	v_cvt_pk_bf16_f32 v114, v50, v51
	v_cvt_pk_bf16_f32 v115, v52, v53
	v_cvt_pk_bf16_f32 v116, v54, v55
	v_cvt_pk_bf16_f32 v117, v56, v57
	v_cvt_pk_bf16_f32 v118, v58, v59
	v_cvt_pk_bf16_f32 v119, v60, v61
	v_cvt_pk_bf16_f32 v120, v62, v63
	v_cvt_pk_bf16_f32 v121, v64, v65
	v_add_f32_e32 v162, v162, v0
	s_waitcnt lgkmcnt(0)
	s_barrier
	v_mfma_f32_32x32x16_bf16 v[2:17], v[164:167], v[106:109], v[2:17]
	s_setprio 1
	v_add3_u32 v0, s58, v152, v153
	s_waitcnt vmcnt(5)
	ds_write_b128 v0, v[98:101]
	v_mfma_f32_32x32x16_bf16 v[18:33], v[168:171], v[106:109], v[18:33]
	v_add3_u32 v0, s58, v154, v155
	s_waitcnt vmcnt(4)
	ds_write_b128 v0, v[94:97]
	v_mfma_f32_32x32x16_bf16 v[2:17], v[172:175], v[110:113], v[2:17]
	v_add3_u32 v0, s58, v156, v140
	s_waitcnt vmcnt(3)
	ds_write_b128 v0, v[102:105] offset:13312
	v_add_u32_e32 v249, s57, v157
	v_mfma_f32_32x32x16_bf16 v[18:33], v[176:179], v[110:113], v[18:33]
	ds_read_b128 v[236:239], v249
	ds_read_b128 v[240:243], v249 offset:6656
	ds_read_b128 v[244:247], v249 offset:32
	v_mfma_f32_32x32x16_bf16 v[2:17], v[180:183], v[114:117], v[2:17]
	ds_read_b128 v[164:167], v249 offset:6688
	ds_read_b128 v[168:171], v249 offset:64
	ds_read_b128 v[172:175], v249 offset:6720
	v_mfma_f32_32x32x16_bf16 v[18:33], v[220:223], v[114:117], v[18:33]
	ds_read_b128 v[176:179], v249 offset:96
	ds_read_b128 v[180:183], v249 offset:6752
	ds_read_b128 v[220:223], v249 offset:128
	v_mfma_f32_32x32x16_bf16 v[2:17], v[224:227], v[118:121], v[2:17]
	ds_read_b128 v[224:227], v249 offset:6784
	s_add_i32 s59, s59, 2
	s_mov_b32 s0, s58
	v_mfma_f32_32x32x16_bf16 v[18:33], v[232:235], v[118:121], v[18:33]
	ds_read_b128 v[232:235], v249 offset:160
	s_mov_b32 s58, s57
	s_mov_b32 s57, s60
	s_mov_b32 s60, s0
	s_addk_i32 s54, 0x80
	s_waitcnt lgkmcnt(9)
	v_mfma_f32_32x32x16_bf16 v[34:49], v[236:239], v[196:199], v[66:81]
	ds_read_b128 v[236:239], v249 offset:6816
	s_add_i32 s1, s59, 3
	s_cmp_lt_u32 s1, s49
	v_mfma_f32_32x32x16_bf16 v[50:65], v[240:243], v[196:199], v[66:81]
	s_cselect_b32 s1, s1, s50
	s_lshl_b32 s8, s1, 6
	s_mul_i32 s20, s8, 0x600
	s_waitcnt lgkmcnt(7)
	v_mfma_f32_32x32x16_bf16 v[34:49], v[244:247], v[200:203], v[34:49]
	s_mov_b32 s21, 0
	v_lshl_add_u64 v[94:95], s[20:21], 0, v[186:187]
	v_lshl_add_u64 v[96:97], s[20:21], 0, v[188:189]
	v_mfma_f32_32x32x16_bf16 v[50:65], v[164:167], v[200:203], v[50:65]
	v_lshl_add_u64 v[102:103], s[8:9], 1, v[142:143]
	global_load_dwordx4 v[98:101], v[94:95], off
	s_nop 0
	v_mfma_f32_32x32x16_bf16 v[34:49], v[168:171], v[204:207], v[34:49]
	global_load_dwordx4 v[94:97], v[96:97], off
	global_load_dwordx4 v[102:105], v[102:103], off
	s_waitcnt lgkmcnt(4)
	v_mfma_f32_32x32x16_bf16 v[50:65], v[172:175], v[204:207], v[50:65]
	v_mfma_f32_32x32x16_bf16 v[34:49], v[176:179], v[208:211], v[34:49]
	v_mfma_f32_32x32x16_bf16 v[50:65], v[180:183], v[208:211], v[50:65]
	s_waitcnt lgkmcnt(1)
	v_mfma_f32_32x32x16_bf16 v[34:49], v[220:223], v[212:215], v[34:49]
	v_mfma_f32_32x32x16_bf16 v[50:65], v[224:227], v[212:215], v[50:65]
	v_mfma_f32_32x32x16_bf16 v[34:49], v[232:235], v[216:219], v[34:49]
	s_waitcnt lgkmcnt(0)
	v_mfma_f32_32x32x16_bf16 v[50:65], v[236:239], v[216:219], v[50:65]
	s_setprio 0
	s_add_i32 s4, s55, s59
	s_cmp_lt_i32 s4, -2
	s_waitcnt lgkmcnt(0)
	s_barrier
	s_cbranch_scc1 .Lfm_head
	s_mov_b32 s0, s58
	s_mov_b32 s58, s60
	s_branch .LBB0_1037

.Lfm_a_1047:
	v_add_f32_e32 v163, v163, v0
	v_xor_b32_e32 v66, 0x80000000, v163
	v_sub_f32_e32 v49, v49, v0
	v_sub_f32_e32 v48, v48, v0
	v_sub_f32_e32 v47, v47, v0
	v_sub_f32_e32 v46, v46, v0
	v_sub_f32_e32 v45, v45, v0
	v_sub_f32_e32 v44, v44, v0
	v_sub_f32_e32 v43, v43, v0
	v_sub_f32_e32 v42, v42, v0
	v_sub_f32_e32 v41, v41, v0
	v_sub_f32_e32 v40, v40, v0
	v_sub_f32_e32 v39, v39, v0
	v_sub_f32_e32 v38, v38, v0
	v_sub_f32_e32 v37, v37, v0
	v_sub_f32_e32 v36, v36, v0
	v_sub_f32_e32 v35, v35, v0
	v_sub_f32_e32 v34, v34, v0
	v_sub_f32_e32 v65, v65, v0
	v_sub_f32_e32 v64, v64, v0
	v_sub_f32_e32 v63, v63, v0
	v_sub_f32_e32 v62, v62, v0
	v_sub_f32_e32 v61, v61, v0
	v_sub_f32_e32 v60, v60, v0
	v_sub_f32_e32 v59, v59, v0
	v_sub_f32_e32 v58, v58, v0
	v_sub_f32_e32 v57, v57, v0
	v_sub_f32_e32 v56, v56, v0
	v_sub_f32_e32 v55, v55, v0
	v_sub_f32_e32 v54, v54, v0
	v_sub_f32_e32 v53, v53, v0
	v_sub_f32_e32 v52, v52, v0
	v_sub_f32_e32 v51, v51, v0
	v_sub_f32_e32 v50, v50, v0
	v_mov_b32_e32 v67, v66
	v_mov_b32_e32 v68, v66
	v_mov_b32_e32 v69, v66
	v_mov_b32_e32 v70, v66
	v_mov_b32_e32 v71, v66
	v_mov_b32_e32 v72, v66
	v_mov_b32_e32 v73, v66
	v_mov_b32_e32 v74, v66
	v_mov_b32_e32 v75, v66
	v_mov_b32_e32 v76, v66
	v_mov_b32_e32 v77, v66
	v_mov_b32_e32 v78, v66
	v_mov_b32_e32 v79, v66
	v_mov_b32_e32 v80, v66
	v_mov_b32_e32 v81, v66
	s_branch .Lfm_a_exp
.Lfm_b_resc:
	v_and_b32_e32 v107, 64, v148
	v_xor_b32_e32 v106, 32, v148
	v_add_u32_e32 v107, 64, v107
	v_cmp_lt_i32_e32 vcc, v106, v107
	s_nop 1
	v_cndmask_b32_e32 v106, v148, v106, vcc
	v_lshlrev_b32_e32 v106, 2, v106
	ds_bpermute_b32 v106, v106, v0
	s_waitcnt lgkmcnt(0)
	v_max_f32_e32 v106, v106, v106
	v_max_f32_e32 v0, v0, v106
	v_max_f32_e32 v0, v0, v0
	v_max_f32_e32 v66, 0, v0
	v_exp_f32_e64 v0, -v66
	v_add_f32_e32 v163, v163, v66
	v_sub_f32_e32 v49, v49, v66
	v_sub_f32_e32 v48, v48, v66
	v_sub_f32_e32 v47, v47, v66
	v_sub_f32_e32 v46, v46, v66
	v_sub_f32_e32 v45, v45, v66
	v_sub_f32_e32 v44, v44, v66
	v_sub_f32_e32 v43, v43, v66
	v_sub_f32_e32 v42, v42, v66
	v_sub_f32_e32 v41, v41, v66
	v_sub_f32_e32 v40, v40, v66
	v_sub_f32_e32 v39, v39, v66
	v_sub_f32_e32 v38, v38, v66
	v_sub_f32_e32 v37, v37, v66
	v_sub_f32_e32 v36, v36, v66
	v_sub_f32_e32 v35, v35, v66
	v_sub_f32_e32 v34, v34, v66
	v_sub_f32_e32 v65, v65, v66
	v_sub_f32_e32 v64, v64, v66
	v_sub_f32_e32 v63, v63, v66
	v_sub_f32_e32 v62, v62, v66
	v_sub_f32_e32 v61, v61, v66
	v_sub_f32_e32 v60, v60, v66
	v_sub_f32_e32 v59, v59, v66
	v_sub_f32_e32 v58, v58, v66
	v_sub_f32_e32 v57, v57, v66
	v_sub_f32_e32 v56, v56, v66
	v_sub_f32_e32 v55, v55, v66
	v_sub_f32_e32 v54, v54, v66
	v_sub_f32_e32 v53, v53, v66
	v_sub_f32_e32 v52, v52, v66
	v_sub_f32_e32 v51, v51, v66
	v_sub_f32_e32 v50, v50, v66
	v_xor_b32_e32 v66, 0x80000000, v163
	v_mov_b32_e32 v67, v66
	v_mov_b32_e32 v68, v66
	v_mov_b32_e32 v69, v66
	v_mov_b32_e32 v70, v66
	v_mov_b32_e32 v71, v66
	v_mov_b32_e32 v72, v66
	v_mov_b32_e32 v73, v66
	v_mov_b32_e32 v74, v66
	v_mov_b32_e32 v75, v66
	v_mov_b32_e32 v76, v66
	v_mov_b32_e32 v77, v66
	v_mov_b32_e32 v78, v66
	v_mov_b32_e32 v79, v66
	v_mov_b32_e32 v80, v66
	v_mov_b32_e32 v81, v66
	v_pk_mul_f32 v[32:33], v[32:33], v[0:1] op_sel_hi:[1,0]
	v_pk_mul_f32 v[30:31], v[30:31], v[0:1] op_sel_hi:[1,0]
	v_pk_mul_f32 v[28:29], v[28:29], v[0:1] op_sel_hi:[1,0]
	v_pk_mul_f32 v[26:27], v[26:27], v[0:1] op_sel_hi:[1,0]
	v_pk_mul_f32 v[24:25], v[24:25], v[0:1] op_sel_hi:[1,0]
	v_pk_mul_f32 v[22:23], v[22:23], v[0:1] op_sel_hi:[1,0]
	v_pk_mul_f32 v[20:21], v[20:21], v[0:1] op_sel_hi:[1,0]
	v_pk_mul_f32 v[18:19], v[18:19], v[0:1] op_sel_hi:[1,0]
	v_pk_mul_f32 v[16:17], v[16:17], v[0:1] op_sel_hi:[1,0]
	v_pk_mul_f32 v[14:15], v[14:15], v[0:1] op_sel_hi:[1,0]
	v_pk_mul_f32 v[12:13], v[12:13], v[0:1] op_sel_hi:[1,0]
	v_pk_mul_f32 v[10:11], v[10:11], v[0:1] op_sel_hi:[1,0]
	v_pk_mul_f32 v[8:9], v[8:9], v[0:1] op_sel_hi:[1,0]
	v_pk_mul_f32 v[6:7], v[6:7], v[0:1] op_sel_hi:[1,0]
	v_pk_mul_f32 v[4:5], v[4:5], v[0:1] op_sel_hi:[1,0]
	v_pk_mul_f32 v[2:3], v[2:3], v[0:1] op_sel_hi:[1,0]
	v_mul_f32_e32 v162, v162, v0
	s_branch .Lfm_b_exp
